# row phases: write-through (sc1) stores so the barrier's L2 write-back after the streaming phases is clean
# baseline (speedup 1.0000x reference)
.LBB0_19:
	s_or_b64 exec, exec, s[8:9]
	v_mov_b32_e32 v88, v10
	v_mov_b32_e32 v89, v14
	v_pk_mul_f32 v[88:89], v[88:89], v[88:89]
	v_mov_b32_e32 v100, v11
	v_mov_b32_e32 v101, v15
	v_pk_fma_f32 v[88:89], v[100:101], v[100:101], v[88:89]
	v_mov_b32_e32 v100, v12
	v_mov_b32_e32 v101, v16
	v_pk_fma_f32 v[88:89], v[100:101], v[100:101], v[88:89]
	v_mov_b32_e32 v100, v13
	v_mov_b32_e32 v101, v17
	v_pk_fma_f32 v[88:89], v[100:101], v[100:101], v[88:89]
	v_mov_b32_e32 v100, v2
	v_mov_b32_e32 v101, v6
	v_pk_mul_f32 v[100:101], v[100:101], v[100:101]
	v_mov_b32_e32 v102, v3
	v_mov_b32_e32 v103, v7
	v_pk_fma_f32 v[100:101], v[102:103], v[102:103], v[100:101]
	v_mov_b32_e32 v102, v4
	v_mov_b32_e32 v103, v8
	v_pk_fma_f32 v[100:101], v[102:103], v[102:103], v[100:101]
	v_mov_b32_e32 v102, v5
	v_mov_b32_e32 v103, v9
	v_pk_fma_f32 v[100:101], v[102:103], v[102:103], v[100:101]
	v_add_f32_e32 v88, v88, v89
	v_add_f32_e32 v88, v101, v88
	v_add_f32_e32 v88, v100, v88
	ds_bpermute_b32 v89, v93, v88
	s_and_b64 s[0:1], exec, vcc
	v_pk_add_f32 v[100:101], v[24:25], 1.0 op_sel_hi:[1,0]
	s_or_b64 s[6:7], s[0:1], s[6:7]
	s_waitcnt lgkmcnt(0)
	v_add_f32_e32 v88, v88, v89
	ds_bpermute_b32 v89, v94, v88
	s_waitcnt lgkmcnt(0)
	v_add_f32_e32 v88, v88, v89
	ds_bpermute_b32 v89, v95, v88
	s_waitcnt lgkmcnt(0)
	v_add_f32_e32 v88, v88, v89
	ds_bpermute_b32 v89, v96, v88
	s_waitcnt lgkmcnt(0)
	v_add_f32_e32 v88, v88, v89
	ds_bpermute_b32 v89, v97, v88
	s_waitcnt lgkmcnt(0)
	v_add_f32_e32 v88, v88, v89
	ds_bpermute_b32 v89, v98, v88
	s_waitcnt lgkmcnt(0)
	v_add_f32_e32 v88, v88, v89
	v_fmamk_f32 v88, v88, 0x3a800000, v167
	v_mul_f32_e32 v89, 0x4b800000, v88
	v_cmp_gt_f32_e32 vcc, s70, v88
	s_nop 1
	v_cndmask_b32_e32 v88, v88, v89, vcc
	v_rsq_f32_e32 v102, v88
	v_pk_add_f32 v[88:89], v[22:23], 1.0 op_sel_hi:[1,0]
	v_mul_f32_e32 v103, 0x45800000, v102
	v_cndmask_b32_e32 v102, v102, v103, vcc
	v_pk_mul_f32 v[14:15], v[14:15], v[102:103] op_sel_hi:[1,0]
	v_pk_mul_f32 v[16:17], v[16:17], v[102:103] op_sel_hi:[1,0]
	v_pk_mul_f32 v[14:15], v[18:19], v[14:15]
	v_pk_mul_f32 v[16:17], v[20:21], v[16:17]
	v_pk_fma_f32 v[14:15], v[88:89], v[14:15], v[30:31]
	v_pk_fma_f32 v[16:17], v[100:101], v[16:17], v[32:33]
	v_cvt_pk_bf16_f32 v14, v14, v15
	v_cvt_pk_bf16_f32 v15, v16, v17
	v_pk_mul_f32 v[10:11], v[10:11], v[102:103] op_sel_hi:[1,0]
	global_store_dwordx2 v[86:87], v[14:15], off offset:-1540 sc1
	v_pk_add_f32 v[14:15], v[34:35], 1.0 op_sel_hi:[1,0]
	v_pk_mul_f32 v[10:11], v[26:27], v[10:11]
	v_pk_mul_f32 v[12:13], v[12:13], v[102:103] op_sel_hi:[1,0]
	v_pk_fma_f32 v[10:11], v[14:15], v[10:11], v[38:39]
	v_pk_add_f32 v[14:15], v[36:37], 1.0 op_sel_hi:[1,0]
	v_pk_mul_f32 v[12:13], v[28:29], v[12:13]
	v_cvt_pk_bf16_f32 v10, v10, v11
	v_pk_fma_f32 v[12:13], v[14:15], v[12:13], v[40:41]
	v_pk_mul_f32 v[6:7], v[6:7], v[102:103] op_sel_hi:[1,0]
	v_cvt_pk_bf16_f32 v11, v12, v13
	global_store_dwordx2 v[86:87], v[10:11], off offset:-1028 sc1
	v_pk_add_f32 v[10:11], v[46:47], 1.0 op_sel_hi:[1,0]
	v_pk_mul_f32 v[6:7], v[42:43], v[6:7]
	v_pk_mul_f32 v[8:9], v[8:9], v[102:103] op_sel_hi:[1,0]
	v_pk_fma_f32 v[6:7], v[10:11], v[6:7], v[54:55]
	v_pk_add_f32 v[10:11], v[48:49], 1.0 op_sel_hi:[1,0]
	v_pk_mul_f32 v[8:9], v[44:45], v[8:9]
	v_cvt_pk_bf16_f32 v6, v6, v7
	v_pk_fma_f32 v[8:9], v[10:11], v[8:9], v[56:57]
	v_pk_mul_f32 v[2:3], v[2:3], v[102:103] op_sel_hi:[1,0]
	v_cvt_pk_bf16_f32 v7, v8, v9
	global_store_dwordx2 v[86:87], v[6:7], off offset:-516 sc1
	v_pk_add_f32 v[6:7], v[58:59], 1.0 op_sel_hi:[1,0]
	v_pk_mul_f32 v[2:3], v[50:51], v[2:3]
	v_pk_mul_f32 v[4:5], v[4:5], v[102:103] op_sel_hi:[1,0]
	v_pk_fma_f32 v[2:3], v[6:7], v[2:3], v[62:63]
	v_pk_add_f32 v[6:7], v[60:61], 1.0 op_sel_hi:[1,0]
	v_pk_mul_f32 v[4:5], v[52:53], v[4:5]
	v_cvt_pk_bf16_f32 v2, v2, v3
	v_pk_fma_f32 v[4:5], v[6:7], v[4:5], v[64:65]
	v_mov_b64_e32 v[88:89], v[90:91]
	v_cvt_pk_bf16_f32 v3, v4, v5
	global_store_dwordx2 v[86:87], v[2:3], off offset:-4 sc1
	v_lshl_add_u64 v[86:87], v[86:87], 0, s[84:85]
	s_waitcnt vmcnt(4)
	v_mov_b64_e32 v[4:5], v[80:81]
	v_mov_b64_e32 v[2:3], v[78:79]
	v_mov_b64_e32 v[8:9], v[76:77]
	v_mov_b64_e32 v[6:7], v[74:75]
	v_mov_b64_e32 v[12:13], v[72:73]
	v_mov_b64_e32 v[10:11], v[70:71]
	v_mov_b64_e32 v[16:17], v[68:69]
	v_mov_b64_e32 v[14:15], v[66:67]
	s_andn2_b64 exec, exec, s[6:7]
	s_cbranch_execz .LBB0_26

.LBB0_37:
	s_or_b64 exec, exec, s[18:19]
	v_and_b32_e32 v99, 0xffff0000, v82
	v_and_b32_e32 v101, 0xffff0000, v80
	v_lshlrev_b32_e32 v98, 16, v82
	v_lshlrev_b32_e32 v100, 16, v80
	v_mov_b32_e32 v108, v101
	v_mov_b32_e32 v109, v99
	v_lshlrev_b32_e32 v82, 16, v83
	v_lshlrev_b32_e32 v80, 16, v81
	v_mov_b32_e32 v106, v100
	v_mov_b32_e32 v107, v98
	v_pk_mul_f32 v[108:109], v[108:109], v[108:109]
	v_and_b32_e32 v83, 0xffff0000, v83
	v_and_b32_e32 v81, 0xffff0000, v81
	v_pk_fma_f32 v[106:107], v[106:107], v[106:107], v[108:109]
	v_mov_b32_e32 v108, v80
	v_mov_b32_e32 v109, v82
	v_and_b32_e32 v103, 0xffff0000, v78
	v_and_b32_e32 v105, 0xffff0000, v76
	v_mov_b32_e32 v110, v81
	v_mov_b32_e32 v111, v83
	v_pk_fma_f32 v[106:107], v[108:109], v[108:109], v[106:107]
	v_lshlrev_b32_e32 v102, 16, v78
	v_lshlrev_b32_e32 v104, 16, v76
	v_pk_fma_f32 v[106:107], v[110:111], v[110:111], v[106:107]
	v_mov_b32_e32 v110, v105
	v_mov_b32_e32 v111, v103
	v_lshlrev_b32_e32 v78, 16, v79
	v_lshlrev_b32_e32 v76, 16, v77
	v_mov_b32_e32 v108, v104
	v_mov_b32_e32 v109, v102
	v_pk_mul_f32 v[110:111], v[110:111], v[110:111]
	v_and_b32_e32 v79, 0xffff0000, v79
	v_and_b32_e32 v77, 0xffff0000, v77
	v_pk_fma_f32 v[108:109], v[108:109], v[108:109], v[110:111]
	v_mov_b32_e32 v110, v76
	v_mov_b32_e32 v111, v78
	v_mov_b32_e32 v112, v77
	v_mov_b32_e32 v113, v79
	v_pk_fma_f32 v[108:109], v[110:111], v[110:111], v[108:109]
	v_add_f32_e32 v106, v106, v107
	v_pk_fma_f32 v[108:109], v[112:113], v[112:113], v[108:109]
	s_and_b64 s[0:1], exec, vcc
	v_add_f32_e32 v106, v109, v106
	v_add_f32_e32 v106, v108, v106
	ds_bpermute_b32 v107, v0, v106
	s_or_b64 s[8:9], s[0:1], s[8:9]
	s_mov_b64 s[0:1], 0x1000
	v_lshl_add_u64 v[74:75], v[74:75], 0, s[84:85]
	s_waitcnt lgkmcnt(0)
	v_add_f32_e32 v106, v106, v107
	ds_bpermute_b32 v107, v67, v106
	s_waitcnt lgkmcnt(0)
	v_add_f32_e32 v106, v106, v107
	ds_bpermute_b32 v107, v93, v106
	s_waitcnt lgkmcnt(0)
	v_add_f32_e32 v106, v106, v107
	ds_bpermute_b32 v107, v94, v106
	s_waitcnt lgkmcnt(0)
	v_add_f32_e32 v106, v106, v107
	ds_bpermute_b32 v107, v95, v106
	s_waitcnt lgkmcnt(0)
	v_add_f32_e32 v106, v106, v107
	ds_bpermute_b32 v107, v96, v106
	s_waitcnt lgkmcnt(0)
	v_add_f32_e32 v106, v106, v107
	v_fmamk_f32 v106, v106, 0x3a800000, v167
	v_cmp_gt_f32_e32 vcc, s70, v106
	v_mul_f32_e32 v107, 0x4b800000, v106
	s_nop 0
	v_cndmask_b32_e32 v106, v106, v107, vcc
	v_rsq_f32_e32 v106, v106
	s_nop 0
	v_mul_f32_e32 v107, 0x45800000, v106
	v_cndmask_b32_e32 v106, v106, v107, vcc
	v_pk_mul_f32 v[98:99], v[106:107], v[98:99] op_sel_hi:[0,1]
	v_pk_mul_f32 v[82:83], v[106:107], v[82:83] op_sel_hi:[0,1]
	v_pk_mul_f32 v[98:99], v[18:19], v[98:99]
	v_pk_mul_f32 v[82:83], v[20:21], v[82:83]
	v_pk_fma_f32 v[2:3], v[30:31], v[98:99], v[2:3]
	v_pk_fma_f32 v[4:5], v[32:33], v[82:83], v[4:5]
	global_store_dwordx4 v[72:73], v[2:5], off offset:-4096 sc1
	s_waitcnt vmcnt(4)
	v_mov_b64_e32 v[82:83], v[84:85]
	v_pk_mul_f32 v[2:3], v[106:107], v[100:101] op_sel_hi:[0,1]
	v_pk_mul_f32 v[4:5], v[106:107], v[80:81] op_sel_hi:[0,1]
	v_pk_mul_f32 v[2:3], v[22:23], v[2:3]
	v_pk_mul_f32 v[4:5], v[24:25], v[4:5]
	v_pk_fma_f32 v[2:3], v[26:27], v[2:3], v[6:7]
	v_pk_fma_f32 v[4:5], v[28:29], v[4:5], v[8:9]
	global_store_dwordx4 v[72:73], v[2:5], off offset:-3072 sc1
	s_waitcnt vmcnt(4)
	v_mov_b64_e32 v[80:81], v[86:87]
	v_mov_b64_e32 v[6:7], v[54:55]
	v_pk_mul_f32 v[2:3], v[106:107], v[102:103] op_sel_hi:[0,1]
	v_pk_mul_f32 v[4:5], v[106:107], v[78:79] op_sel_hi:[0,1]
	v_pk_mul_f32 v[2:3], v[38:39], v[2:3]
	v_pk_mul_f32 v[4:5], v[40:41], v[4:5]
	v_pk_fma_f32 v[2:3], v[34:35], v[2:3], v[10:11]
	v_pk_fma_f32 v[4:5], v[36:37], v[4:5], v[12:13]
	global_store_dwordx4 v[72:73], v[2:5], off offset:-2048 sc1
	s_waitcnt vmcnt(4)
	v_mov_b64_e32 v[78:79], v[88:89]
	v_mov_b64_e32 v[8:9], v[56:57]
	v_pk_mul_f32 v[2:3], v[106:107], v[104:105] op_sel_hi:[0,1]
	v_pk_mul_f32 v[4:5], v[106:107], v[76:77] op_sel_hi:[0,1]
	v_pk_mul_f32 v[2:3], v[42:43], v[2:3]
	v_pk_mul_f32 v[4:5], v[44:45], v[4:5]
	v_pk_fma_f32 v[2:3], v[46:47], v[2:3], v[14:15]
	v_pk_fma_f32 v[4:5], v[48:49], v[4:5], v[16:17]
	global_store_dwordx4 v[72:73], v[2:5], off offset:-1024 sc1
	v_lshl_add_u64 v[72:73], v[72:73], 0, s[0:1]
	s_waitcnt vmcnt(4)
	v_mov_b64_e32 v[76:77], v[90:91]
	v_mov_b64_e32 v[2:3], v[50:51]
	v_mov_b64_e32 v[4:5], v[52:53]
	v_mov_b64_e32 v[10:11], v[58:59]
	v_mov_b64_e32 v[12:13], v[60:61]
	v_mov_b64_e32 v[14:15], v[62:63]
	v_mov_b64_e32 v[16:17], v[64:65]
	s_andn2_b64 exec, exec, s[8:9]
	s_cbranch_execz .LBB0_42

.LBB0_46:
	s_or_b64 exec, exec, s[18:19]
	v_and_b32_e32 v149, 0xffff0000, v132
	v_and_b32_e32 v151, 0xffff0000, v130
	v_lshlrev_b32_e32 v148, 16, v132
	v_lshlrev_b32_e32 v150, 16, v130
	v_mov_b32_e32 v160, v151
	v_mov_b32_e32 v161, v149
	v_lshlrev_b32_e32 v132, 16, v133
	v_lshlrev_b32_e32 v130, 16, v131
	v_mov_b32_e32 v158, v150
	v_mov_b32_e32 v159, v148
	v_pk_mul_f32 v[160:161], v[160:161], v[160:161]
	v_and_b32_e32 v133, 0xffff0000, v133
	v_and_b32_e32 v131, 0xffff0000, v131
	v_pk_fma_f32 v[158:159], v[158:159], v[158:159], v[160:161]
	v_mov_b32_e32 v160, v130
	v_mov_b32_e32 v161, v132
	v_and_b32_e32 v153, 0xffff0000, v128
	v_and_b32_e32 v155, 0xffff0000, v126
	v_mov_b32_e32 v162, v131
	v_mov_b32_e32 v163, v133
	v_pk_fma_f32 v[158:159], v[160:161], v[160:161], v[158:159]
	v_lshlrev_b32_e32 v152, 16, v128
	v_lshlrev_b32_e32 v154, 16, v126
	v_pk_fma_f32 v[158:159], v[162:163], v[162:163], v[158:159]
	v_mov_b32_e32 v162, v155
	v_mov_b32_e32 v163, v153
	v_lshlrev_b32_e32 v128, 16, v129
	v_lshlrev_b32_e32 v126, 16, v127
	v_mov_b32_e32 v160, v154
	v_mov_b32_e32 v161, v152
	v_pk_mul_f32 v[162:163], v[162:163], v[162:163]
	v_and_b32_e32 v129, 0xffff0000, v129
	v_and_b32_e32 v127, 0xffff0000, v127
	v_pk_fma_f32 v[160:161], v[160:161], v[160:161], v[162:163]
	v_mov_b32_e32 v162, v126
	v_mov_b32_e32 v163, v128
	v_mov_b32_e32 v164, v127
	v_mov_b32_e32 v165, v129
	v_pk_fma_f32 v[160:161], v[162:163], v[162:163], v[160:161]
	v_add_f32_e32 v157, v158, v159
	v_pk_fma_f32 v[160:161], v[164:165], v[164:165], v[160:161]
	s_nop 0
	v_add_f32_e32 v157, v161, v157
	v_add_f32_e32 v157, v160, v157
	ds_bpermute_b32 v158, v0, v157
	s_waitcnt lgkmcnt(0)
	v_add_f32_e32 v157, v157, v158
	ds_bpermute_b32 v158, v115, v157
	s_waitcnt lgkmcnt(0)
	v_add_f32_e32 v157, v157, v158
	ds_bpermute_b32 v158, v143, v157
	s_waitcnt lgkmcnt(0)
	v_add_f32_e32 v157, v157, v158
	ds_bpermute_b32 v158, v144, v157
	s_waitcnt lgkmcnt(0)
	v_add_f32_e32 v157, v157, v158
	ds_bpermute_b32 v158, v145, v157
	s_waitcnt lgkmcnt(0)
	v_add_f32_e32 v157, v157, v158
	ds_bpermute_b32 v158, v146, v157
	s_waitcnt lgkmcnt(0)
	v_add_f32_e32 v157, v157, v158
	v_fmamk_f32 v157, v157, 0x3a800000, v167
	v_mul_f32_e32 v158, 0x4b800000, v157
	v_cmp_gt_f32_e64 s[0:1], s70, v157
	s_nop 1
	v_cndmask_b32_e64 v157, v157, v158, s[0:1]
	v_rsq_f32_e32 v157, v157
	s_nop 0
	v_mul_f32_e32 v158, 0x45800000, v157
	v_cndmask_b32_e64 v158, v157, v158, s[0:1]
	v_pk_mul_f32 v[132:133], v[158:159], v[132:133] op_sel_hi:[0,1]
	v_pk_mul_f32 v[132:133], v[4:5], v[132:133]
	v_pk_mul_f32 v[128:129], v[158:159], v[128:129] op_sel_hi:[0,1]
	v_pk_mul_f32 v[148:149], v[158:159], v[148:149] op_sel_hi:[0,1]
	v_pk_fma_f32 v[28:29], v[16:17], v[132:133], v[28:29]
	v_pk_mul_f32 v[132:133], v[158:159], v[150:151] op_sel_hi:[0,1]
	v_pk_mul_f32 v[128:129], v[24:25], v[128:129]
	v_pk_mul_f32 v[148:149], v[2:3], v[148:149]
	v_pk_mul_f32 v[132:133], v[6:7], v[132:133]
	v_pk_mul_f32 v[130:131], v[158:159], v[130:131] op_sel_hi:[0,1]
	v_pk_fma_f32 v[36:37], v[20:21], v[128:129], v[36:37]
	v_pk_mul_f32 v[128:129], v[158:159], v[154:155] op_sel_hi:[0,1]
	v_pk_fma_f32 v[26:27], v[14:15], v[148:149], v[26:27]
	v_pk_fma_f32 v[30:31], v[10:11], v[132:133], v[30:31]
	v_pk_mul_f32 v[130:131], v[8:9], v[130:131]
	v_pk_mul_f32 v[128:129], v[42:43], v[128:129]
	v_pk_mul_f32 v[126:127], v[158:159], v[126:127] op_sel_hi:[0,1]
	v_pk_fma_f32 v[32:33], v[12:13], v[130:131], v[32:33]
	v_pk_mul_f32 v[130:131], v[158:159], v[152:153] op_sel_hi:[0,1]
	v_pk_fma_f32 v[38:39], v[46:47], v[128:129], v[38:39]
	v_pk_mul_f32 v[126:127], v[44:45], v[126:127]
	v_mov_b32_e32 v128, v27
	v_mov_b32_e32 v129, v31
	v_pk_mul_f32 v[130:131], v[22:23], v[130:131]
	v_pk_fma_f32 v[40:41], v[48:49], v[126:127], v[40:41]
	v_mov_b32_e32 v126, v26
	v_mov_b32_e32 v127, v30
	v_pk_mul_f32 v[128:129], v[128:129], v[128:129]
	v_pk_fma_f32 v[34:35], v[18:19], v[130:131], v[34:35]
	v_pk_fma_f32 v[126:127], v[126:127], v[126:127], v[128:129]
	v_mov_b32_e32 v128, v28
	v_mov_b32_e32 v129, v32
	v_pk_fma_f32 v[126:127], v[128:129], v[128:129], v[126:127]
	v_mov_b32_e32 v128, v29
	v_mov_b32_e32 v129, v33
	v_mov_b32_e32 v130, v39
	v_mov_b32_e32 v131, v35
	v_pk_fma_f32 v[126:127], v[128:129], v[128:129], v[126:127]
	v_mov_b32_e32 v128, v38
	v_mov_b32_e32 v129, v34
	v_pk_mul_f32 v[130:131], v[130:131], v[130:131]
	v_add_f32_e32 v126, v126, v127
	v_pk_fma_f32 v[128:129], v[128:129], v[128:129], v[130:131]
	v_mov_b32_e32 v130, v40
	v_mov_b32_e32 v131, v36
	v_pk_fma_f32 v[128:129], v[130:131], v[130:131], v[128:129]
	v_mov_b32_e32 v130, v41
	v_mov_b32_e32 v131, v37
	v_pk_fma_f32 v[128:129], v[130:131], v[130:131], v[128:129]
	s_and_b64 s[0:1], exec, vcc
	v_add_f32_e32 v126, v129, v126
	v_add_f32_e32 v126, v128, v126
	ds_bpermute_b32 v127, v0, v126
	global_store_dwordx4 v[124:125], v[26:29], off offset:-4096 sc1
	v_pk_add_f32 v[128:129], v[82:83], 1.0 op_sel_hi:[1,0]
	global_store_dwordx4 v[124:125], v[30:33], off offset:-3072 sc1
	global_store_dwordx4 v[124:125], v[34:37], off offset:-2048 sc1
	global_store_dwordx4 v[124:125], v[38:41], off offset:-1024 sc1
	s_or_b64 s[8:9], s[0:1], s[8:9]
	s_waitcnt lgkmcnt(0)
	v_add_f32_e32 v126, v126, v127
	ds_bpermute_b32 v127, v115, v126
	s_mov_b64 s[0:1], 0x1000
	v_lshl_add_u64 v[124:125], v[124:125], 0, s[0:1]
	s_waitcnt vmcnt(6)
	v_mov_b64_e32 v[130:131], v[136:137]
	v_mov_b64_e32 v[132:133], v[134:135]
	s_waitcnt lgkmcnt(0)
	v_add_f32_e32 v126, v126, v127
	ds_bpermute_b32 v127, v143, v126
	s_waitcnt lgkmcnt(0)
	v_add_f32_e32 v126, v126, v127
	ds_bpermute_b32 v127, v144, v126
	s_waitcnt lgkmcnt(0)
	v_add_f32_e32 v126, v126, v127
	ds_bpermute_b32 v127, v145, v126
	s_waitcnt lgkmcnt(0)
	v_add_f32_e32 v126, v126, v127
	ds_bpermute_b32 v127, v146, v126
	s_waitcnt lgkmcnt(0)
	v_add_f32_e32 v126, v126, v127
	v_fmamk_f32 v126, v126, 0x3a800000, v167
	v_mul_f32_e32 v127, 0x4b800000, v126
	v_cmp_gt_f32_e32 vcc, s70, v126
	s_nop 1
	v_cndmask_b32_e32 v126, v126, v127, vcc
	v_rsq_f32_e32 v126, v126
	s_nop 0
	v_mul_f32_e32 v127, 0x45800000, v126
	v_cndmask_b32_e32 v126, v126, v127, vcc
	v_pk_mul_f32 v[26:27], v[26:27], v[126:127] op_sel_hi:[1,0]
	v_pk_mul_f32 v[28:29], v[28:29], v[126:127] op_sel_hi:[1,0]
	v_pk_mul_f32 v[26:27], v[50:51], v[26:27]
	v_pk_mul_f32 v[28:29], v[52:53], v[28:29]
	v_pk_fma_f32 v[26:27], v[128:129], v[26:27], v[70:71]
	v_pk_add_f32 v[128:129], v[84:85], 1.0 op_sel_hi:[1,0]
	v_cvt_pk_bf16_f32 v26, v26, v27
	v_pk_fma_f32 v[28:29], v[128:129], v[28:29], v[72:73]
	s_waitcnt vmcnt(5)
	v_mov_b64_e32 v[128:129], v[138:139]
	v_cvt_pk_bf16_f32 v27, v28, v29
	v_pk_mul_f32 v[28:29], v[30:31], v[126:127] op_sel_hi:[1,0]
	global_store_dwordx2 v[122:123], v[26:27], off sc1
	v_pk_add_f32 v[26:27], v[58:59], 1.0 op_sel_hi:[1,0]
	v_pk_mul_f32 v[28:29], v[54:55], v[28:29]
	v_pk_mul_f32 v[30:31], v[32:33], v[126:127] op_sel_hi:[1,0]
	v_pk_fma_f32 v[26:27], v[26:27], v[28:29], v[62:63]
	v_pk_add_f32 v[28:29], v[60:61], 1.0 op_sel_hi:[1,0]
	v_pk_mul_f32 v[30:31], v[56:57], v[30:31]
	v_cvt_pk_bf16_f32 v26, v26, v27
	v_pk_fma_f32 v[28:29], v[28:29], v[30:31], v[64:65]
	v_pk_mul_f32 v[30:31], v[36:37], v[126:127] op_sel_hi:[1,0]
	v_cvt_pk_bf16_f32 v27, v28, v29
	v_pk_mul_f32 v[28:29], v[34:35], v[126:127] op_sel_hi:[1,0]
	global_store_dwordx2 v[122:123], v[26:27], off offset:512 sc1
	v_pk_add_f32 v[26:27], v[66:67], 1.0 op_sel_hi:[1,0]
	v_pk_mul_f32 v[28:29], v[78:79], v[28:29]
	v_pk_mul_f32 v[30:31], v[80:81], v[30:31]
	v_pk_fma_f32 v[26:27], v[26:27], v[28:29], v[74:75]
	v_pk_add_f32 v[28:29], v[68:69], 1.0 op_sel_hi:[1,0]
	v_cvt_pk_bf16_f32 v26, v26, v27
	v_pk_fma_f32 v[28:29], v[28:29], v[30:31], v[76:77]
	v_pk_mul_f32 v[30:31], v[40:41], v[126:127] op_sel_hi:[1,0]
	v_cvt_pk_bf16_f32 v27, v28, v29
	v_pk_mul_f32 v[28:29], v[38:39], v[126:127] op_sel_hi:[1,0]
	global_store_dwordx2 v[122:123], v[26:27], off offset:1024 sc1
	v_pk_add_f32 v[26:27], v[90:91], 1.0 op_sel_hi:[1,0]
	v_pk_mul_f32 v[28:29], v[86:87], v[28:29]
	v_pk_mul_f32 v[30:31], v[88:89], v[30:31]
	v_pk_fma_f32 v[26:27], v[26:27], v[28:29], v[94:95]
	v_pk_add_f32 v[28:29], v[92:93], 1.0 op_sel_hi:[1,0]
	v_cvt_pk_bf16_f32 v26, v26, v27
	v_pk_fma_f32 v[28:29], v[28:29], v[30:31], v[96:97]
	s_waitcnt vmcnt(7)
	v_mov_b64_e32 v[126:127], v[140:141]
	v_cvt_pk_bf16_f32 v27, v28, v29
	global_store_dwordx2 v[122:123], v[26:27], off offset:1536 sc1
	v_lshl_add_u64 v[122:123], v[122:123], 0, s[84:85]
	v_mov_b64_e32 v[26:27], v[98:99]
	v_mov_b64_e32 v[28:29], v[100:101]
	v_mov_b64_e32 v[30:31], v[102:103]
	v_mov_b64_e32 v[32:33], v[104:105]
	v_mov_b64_e32 v[34:35], v[106:107]
	v_mov_b64_e32 v[36:37], v[108:109]
	v_mov_b64_e32 v[38:39], v[110:111]
	v_mov_b64_e32 v[40:41], v[112:113]
	s_andn2_b64 exec, exec, s[8:9]
	s_cbranch_execz .LBB0_51

.LBB0_156:
	s_or_b64 exec, exec, s[18:19]
	v_and_b32_e32 v159, 0xffff0000, v136
	v_and_b32_e32 v161, 0xffff0000, v134
	v_lshlrev_b32_e32 v158, 16, v136
	v_lshlrev_b32_e32 v160, 16, v134
	v_mov_b32_e32 v178, v161
	v_mov_b32_e32 v179, v159
	v_lshlrev_b32_e32 v136, 16, v137
	v_lshlrev_b32_e32 v134, 16, v135
	v_mov_b32_e32 v176, v160
	v_mov_b32_e32 v177, v158
	v_pk_mul_f32 v[178:179], v[178:179], v[178:179]
	v_and_b32_e32 v137, 0xffff0000, v137
	v_and_b32_e32 v135, 0xffff0000, v135
	v_pk_fma_f32 v[176:177], v[176:177], v[176:177], v[178:179]
	v_mov_b32_e32 v178, v134
	v_mov_b32_e32 v179, v136
	v_and_b32_e32 v163, 0xffff0000, v132
	v_and_b32_e32 v165, 0xffff0000, v130
	v_mov_b32_e32 v194, v135
	v_mov_b32_e32 v195, v137
	v_pk_fma_f32 v[176:177], v[178:179], v[178:179], v[176:177]
	v_lshlrev_b32_e32 v162, 16, v132
	v_lshlrev_b32_e32 v164, 16, v130
	v_pk_fma_f32 v[176:177], v[194:195], v[194:195], v[176:177]
	v_mov_b32_e32 v194, v165
	v_mov_b32_e32 v195, v163
	v_lshlrev_b32_e32 v132, 16, v133
	v_lshlrev_b32_e32 v130, 16, v131
	v_mov_b32_e32 v178, v164
	v_mov_b32_e32 v179, v162
	v_pk_mul_f32 v[194:195], v[194:195], v[194:195]
	v_and_b32_e32 v133, 0xffff0000, v133
	v_and_b32_e32 v131, 0xffff0000, v131
	v_pk_fma_f32 v[178:179], v[178:179], v[178:179], v[194:195]
	v_mov_b32_e32 v194, v130
	v_mov_b32_e32 v195, v132
	v_mov_b32_e32 v196, v131
	v_mov_b32_e32 v197, v133
	v_pk_fma_f32 v[178:179], v[194:195], v[194:195], v[178:179]
	v_add_f32_e32 v128, v176, v177
	v_pk_fma_f32 v[178:179], v[196:197], v[196:197], v[178:179]
	v_readlane_b32 s6, v255, 20
	v_add_f32_e32 v128, v179, v128
	v_add_f32_e32 v128, v178, v128
	ds_bpermute_b32 v139, v129, v128
	v_readlane_b32 s7, v255, 21
	v_lshl_add_u64 v[126:127], v[126:127], 0, 1
	s_waitcnt lgkmcnt(0)
	v_add_f32_e32 v128, v128, v139
	ds_bpermute_b32 v139, v149, v128
	s_waitcnt lgkmcnt(0)
	v_add_f32_e32 v128, v128, v139
	ds_bpermute_b32 v139, v150, v128
	s_waitcnt lgkmcnt(0)
	v_add_f32_e32 v128, v128, v139
	ds_bpermute_b32 v139, v151, v128
	s_waitcnt lgkmcnt(0)
	v_add_f32_e32 v128, v128, v139
	ds_bpermute_b32 v139, v152, v128
	s_waitcnt lgkmcnt(0)
	v_add_f32_e32 v128, v128, v139
	ds_bpermute_b32 v139, v153, v128
	s_waitcnt lgkmcnt(0)
	v_add_f32_e32 v128, v128, v139
	v_fmamk_f32 v128, v128, 0x3a800000, v167
	v_mul_f32_e32 v139, 0x4b800000, v128
	v_cmp_gt_f32_e32 vcc, s70, v128
	s_nop 1
	v_cndmask_b32_e32 v128, v128, v139, vcc
	v_rsq_f32_e32 v128, v128
	s_nop 0
	v_mul_f32_e32 v139, 0x45800000, v128
	v_cndmask_b32_e32 v128, v128, v139, vcc
	v_pk_mul_f32 v[136:137], v[128:129], v[136:137] op_sel_hi:[0,1]
	v_pk_mul_f32 v[136:137], v[4:5], v[136:137]
	v_pk_mul_f32 v[132:133], v[128:129], v[132:133] op_sel_hi:[0,1]
	v_pk_mul_f32 v[158:159], v[128:129], v[158:159] op_sel_hi:[0,1]
	v_pk_fma_f32 v[24:25], v[8:9], v[136:137], v[24:25]
	v_pk_mul_f32 v[136:137], v[128:129], v[160:161] op_sel_hi:[0,1]
	v_pk_mul_f32 v[132:133], v[20:21], v[132:133]
	v_pk_mul_f32 v[158:159], v[2:3], v[158:159]
	v_pk_mul_f32 v[136:137], v[10:11], v[136:137]
	v_pk_mul_f32 v[134:135], v[128:129], v[134:135] op_sel_hi:[0,1]
	v_pk_fma_f32 v[32:33], v[40:41], v[132:133], v[32:33]
	v_pk_mul_f32 v[132:133], v[128:129], v[164:165] op_sel_hi:[0,1]
	v_pk_fma_f32 v[22:23], v[6:7], v[158:159], v[22:23]
	v_pk_fma_f32 v[26:27], v[14:15], v[136:137], v[26:27]
	v_pk_mul_f32 v[134:135], v[12:13], v[134:135]
	v_pk_mul_f32 v[132:133], v[42:43], v[132:133]
	v_pk_mul_f32 v[130:131], v[128:129], v[130:131] op_sel_hi:[0,1]
	v_pk_fma_f32 v[28:29], v[16:17], v[134:135], v[28:29]
	v_pk_mul_f32 v[134:135], v[128:129], v[162:163] op_sel_hi:[0,1]
	v_pk_fma_f32 v[34:35], v[46:47], v[132:133], v[34:35]
	v_pk_mul_f32 v[130:131], v[44:45], v[130:131]
	v_mov_b32_e32 v132, v23
	v_mov_b32_e32 v133, v27
	v_pk_mul_f32 v[134:135], v[18:19], v[134:135]
	v_pk_fma_f32 v[36:37], v[48:49], v[130:131], v[36:37]
	v_mov_b32_e32 v130, v22
	v_mov_b32_e32 v131, v26
	v_pk_mul_f32 v[132:133], v[132:133], v[132:133]
	v_pk_fma_f32 v[30:31], v[38:39], v[134:135], v[30:31]
	v_pk_fma_f32 v[130:131], v[130:131], v[130:131], v[132:133]
	v_mov_b32_e32 v132, v24
	v_mov_b32_e32 v133, v28
	v_pk_fma_f32 v[130:131], v[132:133], v[132:133], v[130:131]
	v_mov_b32_e32 v132, v25
	v_mov_b32_e32 v133, v29
	v_mov_b32_e32 v134, v35
	v_mov_b32_e32 v135, v31
	v_pk_fma_f32 v[130:131], v[132:133], v[132:133], v[130:131]
	v_mov_b32_e32 v132, v34
	v_mov_b32_e32 v133, v30
	v_pk_mul_f32 v[134:135], v[134:135], v[134:135]
	v_add_f32_e32 v128, v130, v131
	v_pk_fma_f32 v[132:133], v[132:133], v[132:133], v[134:135]
	v_mov_b32_e32 v134, v36
	v_mov_b32_e32 v135, v32
	v_pk_fma_f32 v[132:133], v[134:135], v[134:135], v[132:133]
	v_mov_b32_e32 v134, v37
	v_mov_b32_e32 v135, v33
	v_pk_fma_f32 v[132:133], v[134:135], v[134:135], v[132:133]
	s_waitcnt vmcnt(2)
	v_mov_b64_e32 v[134:135], v[142:143]
	v_add_f32_e32 v128, v133, v128
	v_add_f32_e32 v128, v132, v128
	ds_bpermute_b32 v130, v129, v128
	v_mov_b64_e32 v[136:137], v[140:141]
	s_waitcnt lgkmcnt(0)
	v_add_f32_e32 v128, v128, v130
	ds_bpermute_b32 v130, v149, v128
	s_waitcnt lgkmcnt(0)
	v_add_f32_e32 v128, v128, v130
	ds_bpermute_b32 v130, v150, v128
	s_waitcnt lgkmcnt(0)
	v_add_f32_e32 v128, v128, v130
	ds_bpermute_b32 v130, v151, v128
	s_waitcnt lgkmcnt(0)
	v_add_f32_e32 v128, v128, v130
	ds_bpermute_b32 v130, v152, v128
	s_waitcnt lgkmcnt(0)
	v_add_f32_e32 v128, v128, v130
	ds_bpermute_b32 v132, v153, v128
	v_lshl_add_u64 v[130:131], s[6:7], 0, v[124:125]
	global_store_dwordx4 v[130:131], v[22:25], off sc1
	global_store_dwordx4 v[130:131], v[26:29], off offset:1024 sc1
	global_store_dwordx4 v[130:131], v[30:33], off offset:2048 sc1
	global_store_dwordx4 v[130:131], v[34:37], off offset:3072 sc1
	v_lshl_add_u64 v[124:125], v[124:125], 0, s[16:17]
	s_waitcnt lgkmcnt(0)
	v_add_f32_e32 v128, v128, v132
	v_fmamk_f32 v128, v128, 0x3a800000, v167
	v_mul_f32_e32 v132, 0x4b800000, v128
	v_cmp_gt_f32_e32 vcc, s70, v128
	s_nop 1
	v_cndmask_b32_e32 v128, v128, v132, vcc
	v_rsq_f32_e32 v128, v128
	s_waitcnt vmcnt(5)
	v_mov_b64_e32 v[132:133], v[144:145]
	v_mul_f32_e32 v130, 0x45800000, v128
	v_cndmask_b32_e32 v128, v128, v130, vcc
	v_pk_mul_f32 v[22:23], v[22:23], v[128:129] op_sel_hi:[1,0]
	v_pk_add_f32 v[130:131], v[54:55], 1.0 op_sel_hi:[1,0]
	v_pk_mul_f32 v[22:23], v[50:51], v[22:23]
	v_pk_mul_f32 v[24:25], v[24:25], v[128:129] op_sel_hi:[1,0]
	v_pk_fma_f32 v[22:23], v[130:131], v[22:23], v[62:63]
	v_pk_add_f32 v[130:131], v[56:57], 1.0 op_sel_hi:[1,0]
	v_pk_mul_f32 v[24:25], v[52:53], v[24:25]
	v_cvt_pk_bf16_f32 v22, v22, v23
	v_pk_fma_f32 v[24:25], v[130:131], v[24:25], v[64:65]
	v_cmp_ge_i32_e32 vcc, v138, v148
	v_cvt_pk_bf16_f32 v23, v24, v25
	v_pk_mul_f32 v[24:25], v[26:27], v[128:129] op_sel_hi:[1,0]
	global_store_dwordx2 v[122:123], v[22:23], off offset:-1540 sc1
	v_pk_add_f32 v[22:23], v[66:67], 1.0 op_sel_hi:[1,0]
	v_pk_mul_f32 v[24:25], v[58:59], v[24:25]
	v_pk_mul_f32 v[26:27], v[28:29], v[128:129] op_sel_hi:[1,0]
	v_pk_fma_f32 v[22:23], v[22:23], v[24:25], v[70:71]
	v_pk_add_f32 v[24:25], v[68:69], 1.0 op_sel_hi:[1,0]
	v_pk_mul_f32 v[26:27], v[60:61], v[26:27]
	v_cvt_pk_bf16_f32 v22, v22, v23
	v_pk_fma_f32 v[24:25], v[24:25], v[26:27], v[72:73]
	v_pk_mul_f32 v[26:27], v[32:33], v[128:129] op_sel_hi:[1,0]
	v_cvt_pk_bf16_f32 v23, v24, v25
	v_pk_mul_f32 v[24:25], v[30:31], v[128:129] op_sel_hi:[1,0]
	global_store_dwordx2 v[122:123], v[22:23], off offset:-1028 sc1
	v_pk_add_f32 v[22:23], v[78:79], 1.0 op_sel_hi:[1,0]
	v_pk_mul_f32 v[24:25], v[74:75], v[24:25]
	v_pk_mul_f32 v[26:27], v[76:77], v[26:27]
	v_pk_fma_f32 v[22:23], v[22:23], v[24:25], v[86:87]
	v_pk_add_f32 v[24:25], v[80:81], 1.0 op_sel_hi:[1,0]
	v_cvt_pk_bf16_f32 v22, v22, v23
	v_pk_fma_f32 v[24:25], v[24:25], v[26:27], v[88:89]
	v_pk_mul_f32 v[26:27], v[36:37], v[128:129] op_sel_hi:[1,0]
	v_cvt_pk_bf16_f32 v23, v24, v25
	v_pk_mul_f32 v[24:25], v[34:35], v[128:129] op_sel_hi:[1,0]
	global_store_dwordx2 v[122:123], v[22:23], off offset:-516 sc1
	v_pk_add_f32 v[22:23], v[90:91], 1.0 op_sel_hi:[1,0]
	v_pk_mul_f32 v[24:25], v[82:83], v[24:25]
	v_pk_mul_f32 v[26:27], v[84:85], v[26:27]
	v_pk_fma_f32 v[22:23], v[22:23], v[24:25], v[94:95]
	v_pk_add_f32 v[24:25], v[92:93], 1.0 op_sel_hi:[1,0]
	v_cvt_pk_bf16_f32 v22, v22, v23
	v_pk_fma_f32 v[24:25], v[24:25], v[26:27], v[96:97]
	s_or_b64 s[8:9], vcc, s[8:9]
	v_cvt_pk_bf16_f32 v23, v24, v25
	global_store_dwordx2 v[122:123], v[22:23], off offset:-4 sc1
	v_lshl_add_u64 v[122:123], v[122:123], 0, s[12:13]
	s_waitcnt vmcnt(8)
	v_mov_b64_e32 v[130:131], v[146:147]
	v_mov_b32_e32 v128, v138
	v_mov_b64_e32 v[22:23], v[110:111]
	v_mov_b64_e32 v[24:25], v[112:113]
	v_mov_b64_e32 v[26:27], v[106:107]
	v_mov_b64_e32 v[28:29], v[108:109]
	v_mov_b64_e32 v[30:31], v[102:103]
	v_mov_b64_e32 v[32:33], v[104:105]
	v_mov_b64_e32 v[34:35], v[98:99]
	v_mov_b64_e32 v[36:37], v[100:101]
	s_andn2_b64 exec, exec, s[8:9]
	s_cbranch_execz .LBB0_165
